# mlA item loop: every wave reads its item's gate values from the up-front slot directly: wave 0's per-item copy and one of the three workgroup barriers per item removed
# baseline (speedup 1.0000x reference)
.LBB0_735:
	s_and_saveexec_b64 s[2:3], s[44:45]
	s_cbranch_execz .LBB0_738
.LBB0_738:
	s_or_b64 exec, exec, s[2:3]
	v_readlane_b32 s2, v254, 33
	s_waitcnt vmcnt(0) lgkmcnt(0)
	v_mov_b32_e32 v16, v88
	v_mov_b32_e32 v17, v89
	v_mov_b32_e32 v18, v90
	v_mov_b32_e32 v19, v91
	v_mov_b32_e32 v20, v92
	v_mov_b32_e32 v21, v93
	v_mov_b32_e32 v22, v94
	v_mov_b32_e32 v23, v95
	v_mov_b32_e32 v24, v96
	v_mov_b32_e32 v25, v97
	v_mov_b32_e32 v26, v98
	v_mov_b32_e32 v27, v99
	s_add_i32 s36, s6, s86
	s_cmpk_gt_i32 s36, 0x87f
	s_cbranch_scc1 .Lmla_pf_none
	s_mul_hi_i32 s7, s36, 0x78787879
	s_lshr_b32 s8, s7, 31
	s_ashr_i32 s40, s7, 5
	s_add_i32 s40, s40, s8
	s_mul_i32 s7, s40, 0x44
	s_sub_i32 s37, s36, s7
	s_mul_i32 s7, s40, 0xffffffbc
	s_add_i32 s10, s36, s7
	s_and_b32 s7, s40, 1
	s_ashr_i32 s39, s40, 3
	s_cmp_gt_i32 s10, 3
	s_cselect_b64 s[10:11], -1, 0
	s_mov_b64 s[8:9], -1
	s_and_b64 vcc, exec, s[10:11]
	s_cbranch_vccz .LBB0_745
	s_cmp_eq_u32 s7, 0
	s_cbranch_scc1 .LBB0_742
	s_mul_i32 s8, s40, 0x1100
	s_add_i32 s8, s8, s18
	v_add_u32_e32 v0, s8, v52
	v_add_u32_e32 v0, 0x10ff, v0
	s_mov_b64 s[8:9], 0

.Lmla_pf_none:
	ds_write_b16 v54, v20 offset:27648
	ds_write_b16_d16_hi v54, v20 offset:27792
	ds_write_b16 v54, v21 offset:27936
	ds_write_b16_d16_hi v54, v21 offset:28080
	ds_write_b16 v54, v22 offset:28224
	ds_write_b16_d16_hi v54, v22 offset:28368
	ds_write_b16 v54, v23 offset:28512
	ds_write_b16_d16_hi v54, v23 offset:28656
	ds_write_b16 v54, v24 offset:36864
	ds_write_b16_d16_hi v54, v24 offset:37008
	ds_write_b16 v54, v25 offset:37152
	ds_write_b16_d16_hi v54, v25 offset:37296
	ds_write_b16 v54, v26 offset:37440
	ds_write_b16_d16_hi v54, v26 offset:37584
	ds_write_b16 v54, v27 offset:37728
	ds_write_b16_d16_hi v54, v27 offset:37872
	s_lshl_b32 s7, s99, 8
	s_add_u32 s7, s7, 0x22400
	v_add_u32_e32 v1, s7, v32
	ds_read_b32 v1, v1
	s_lshl_b32 s7, s99, 2
	s_add_u32 s7, s7, 0x23400
	v_mov_b32_e32 v0, s7
	ds_read_b32 v0, v0
	s_add_i32 s36, s6, s86
	s_cmpk_gt_i32 s36, 0x87f
	s_cselect_b64 s[2:3], -1, 0
	s_and_b64 vcc, exec, s[2:3]
	s_waitcnt lgkmcnt(0)
	v_sub_f32_e32 v0, v1, v0
	v_mul_f32_e32 v0, 0x3fb8aa3b, v0
	v_exp_f32_e32 v0, v0
	v_lshlrev_b32_e32 v1, 16, v16
	v_mul_f32_e32 v1, v0, v1
	v_cvt_pk_bf16_f32 v1, v1, s0
	ds_write_b16 v54, v1 offset:18432
	v_and_b32_e32 v1, 0xffff0000, v16
	v_mul_f32_e32 v1, v0, v1
	v_cvt_pk_bf16_f32 v1, v1, s0
	ds_write_b16 v54, v1 offset:18576
	v_lshlrev_b32_e32 v1, 16, v17
	v_mul_f32_e32 v1, v0, v1
	v_cvt_pk_bf16_f32 v1, v1, s0
	ds_write_b16 v54, v1 offset:18720
	v_and_b32_e32 v1, 0xffff0000, v17
	v_mul_f32_e32 v1, v0, v1
	v_cvt_pk_bf16_f32 v1, v1, s0
	ds_write_b16 v54, v1 offset:18864
	v_lshlrev_b32_e32 v1, 16, v18
	v_mul_f32_e32 v1, v0, v1
	v_cvt_pk_bf16_f32 v1, v1, s0
	ds_write_b16 v54, v1 offset:19008
	v_and_b32_e32 v1, 0xffff0000, v18
	v_mul_f32_e32 v1, v0, v1
	v_cvt_pk_bf16_f32 v1, v1, s0
	ds_write_b16 v54, v1 offset:19152
	v_lshlrev_b32_e32 v1, 16, v19
	v_mul_f32_e32 v1, v0, v1
	v_cvt_pk_bf16_f32 v1, v1, s0
	ds_write_b16 v54, v1 offset:19296
	v_and_b32_e32 v1, 0xffff0000, v19
	v_mul_f32_e32 v0, v0, v1
	v_cvt_pk_bf16_f32 v0, v0, s0
	ds_write_b16 v54, v0 offset:19440
